# grid barrier poll loops: s_sleep 6 -> s_sleep 2 between polls (18 sites)
# speedup vs baseline: 1.0027x; 1.0005x over previous
.LBB0_97:
	s_and_b32 s24, s28, 0xff
	s_mov_b64 s[22:23], -1
	s_cmp_lg_u32 s24, 0
	s_mov_b64 s[26:27], -1
	s_sleep 2
	s_cbranch_scc1 .LBB0_100
	global_load_dword v2, v0, s[14:15] sc1
	s_waitcnt vmcnt(0)
	v_cmp_eq_u32_e32 vcc, 0, v2
	s_cbranch_vccnz .LBB0_102
	s_mov_b64 s[26:27], 0
	s_mov_b64 s[24:25], -1

.LBB0_114:
	s_and_b32 s20, s26, 0xff
	s_cmp_lg_u32 s20, 0
	s_mov_b64 s[22:23], -1
	s_sleep 2
	s_cbranch_scc1 .LBB0_117
	global_load_dword v1, v0, s[14:15] sc1
	s_waitcnt vmcnt(0)
	v_cmp_eq_u32_e32 vcc, 0, v1
	s_cbranch_vccnz .LBB0_119
	s_mov_b64 s[22:23], 0
	s_mov_b64 s[20:21], -1

.LBB0_242:
	s_and_b32 s2, s1, 0xff
	s_mov_b64 s[26:27], -1
	s_cmp_lg_u32 s2, 0
	s_mov_b64 s[30:31], -1
	s_sleep 2
	s_cbranch_scc1 .LBB0_245
	global_load_dword v0, v3, s[18:19] sc1
	s_waitcnt vmcnt(0)
	v_cmp_eq_u32_e32 vcc, 0, v0
	s_cbranch_vccnz .LBB0_247
	s_mov_b64 s[30:31], 0
	s_mov_b64 s[28:29], -1

.LBB0_259:
	s_and_b32 s2, s1, 0xff
	s_mov_b64 s[24:25], -1
	s_cmp_lg_u32 s2, 0
	s_mov_b64 s[28:29], -1
	s_sleep 2
	s_cbranch_scc1 .LBB0_262
	global_load_dword v0, v3, s[18:19] sc1
	s_waitcnt vmcnt(0)
	v_cmp_eq_u32_e32 vcc, 0, v0
	s_cbranch_vccnz .LBB0_264
	s_mov_b64 s[28:29], 0
	s_mov_b64 s[26:27], -1

.LBB0_376:
	s_and_b32 s2, s1, 0xff
	s_mov_b64 s[24:25], -1
	s_cmp_lg_u32 s2, 0
	s_mov_b64 s[28:29], -1
	s_sleep 2
	s_cbranch_scc1 .LBB0_379
	global_load_dword v0, v3, s[16:17] sc1
	s_waitcnt vmcnt(0)
	v_cmp_eq_u32_e32 vcc, 0, v0
	s_cbranch_vccnz .LBB0_381
	s_mov_b64 s[28:29], 0
	s_mov_b64 s[26:27], -1

.LBB0_393:
	s_and_b32 s2, s1, 0xff
	s_mov_b64 s[22:23], -1
	s_cmp_lg_u32 s2, 0
	s_mov_b64 s[26:27], -1
	s_sleep 2
	s_cbranch_scc1 .LBB0_396
	global_load_dword v0, v3, s[16:17] sc1
	s_waitcnt vmcnt(0)
	v_cmp_eq_u32_e32 vcc, 0, v0
	s_cbranch_vccnz .LBB0_398
	s_mov_b64 s[26:27], 0
	s_mov_b64 s[24:25], -1

.LBB0_524:
	s_and_b32 s1, s0, 0xff
	s_mov_b64 s[24:25], -1
	s_cmp_lg_u32 s1, 0
	s_mov_b64 s[28:29], -1
	s_sleep 2
	s_cbranch_scc1 .LBB0_527
	global_load_dword v0, v3, s[16:17] sc1
	s_waitcnt vmcnt(0)
	v_cmp_eq_u32_e32 vcc, 0, v0
	s_cbranch_vccnz .LBB0_529
	s_mov_b64 s[28:29], 0
	s_mov_b64 s[26:27], -1

.LBB0_541:
	s_and_b32 s1, s0, 0xff
	s_mov_b64 s[22:23], -1
	s_cmp_lg_u32 s1, 0
	s_mov_b64 s[26:27], -1
	s_sleep 2
	s_cbranch_scc1 .LBB0_544
	global_load_dword v0, v3, s[16:17] sc1
	s_waitcnt vmcnt(0)
	v_cmp_eq_u32_e32 vcc, 0, v0
	s_cbranch_vccnz .LBB0_546
	s_mov_b64 s[26:27], 0
	s_mov_b64 s[24:25], -1

.LBB0_803:
	s_and_b32 s1, s0, 0xff
	s_mov_b64 s[22:23], -1
	s_cmp_lg_u32 s1, 0
	s_mov_b64 s[26:27], -1
	s_sleep 2
	s_cbranch_scc1 .LBB0_806
	global_load_dword v0, v3, s[14:15] sc1
	s_waitcnt vmcnt(0)
	v_cmp_eq_u32_e32 vcc, 0, v0
	s_cbranch_vccnz .LBB0_808
	s_mov_b64 s[26:27], 0
	s_mov_b64 s[24:25], -1

.LBB0_820:
	s_and_b32 s1, s0, 0xff
	s_mov_b64 s[20:21], -1
	s_cmp_lg_u32 s1, 0
	s_mov_b64 s[24:25], -1
	s_sleep 2
	s_cbranch_scc1 .LBB0_823
	global_load_dword v0, v3, s[14:15] sc1
	s_waitcnt vmcnt(0)
	v_cmp_eq_u32_e32 vcc, 0, v0
	s_cbranch_vccnz .LBB0_825
	s_mov_b64 s[24:25], 0
	s_mov_b64 s[22:23], -1
